# grid barriers 4->5 and 12->13 replaced by per-row-panel sync of the 4 same-XCD work-groups; norm rows remapped to the work-group's own panel
# speedup vs baseline: 1.0106x; 1.0010x over previous
.Ld4_cont:
	s_cmp_gt_i32 s85, 5
	s_cselect_b64 s[4:5], -1, 0
	s_and_b64 s[0:1], s[0:1], s[4:5]
	s_andn2_b64 vcc, exec, s[0:1]
	s_cbranch_vccnz .LBB0_491
	s_waitcnt vmcnt(0)
	s_barrier
	v_readfirstlane_b32 s3, v145
	s_nop 1
	s_cmp_lg_u32 s3, 0
	s_cbranch_scc1 .Lps5_w
	s_and_b32 s99, s2, 7
	s_lshl_b32 s99, s99, 5
	s_lshr_b32 s3, s2, 3
	s_add_u32 s99, s99, s3
	s_lshr_b32 s3, s99, 4
	s_lshl_b32 s3, s3, 2
	s_and_b32 s99, s99, 3
	s_or_b32 s99, s99, s3
	s_lshl_b32 s99, s99, 2
	s_add_u32 s99, s99, 0x4d00
	s_mov_b64 exec, 1
	v_mov_b32_e32 v0, s99
	v_mov_b32_e32 v1, 1
	global_atomic_add v0, v1, s[94:95]
	s_mov_b32 s99, 0
.Lps5_spin:
	global_load_dword v1, v0, s[94:95] sc1
	s_waitcnt vmcnt(0)
	v_cmp_gt_u32_e32 vcc, 4, v1
	s_cbranch_vccz .Lps5_rdy
	s_sleep 1
	s_add_u32 s99, s99, 1
	s_cmp_lt_u32 s99, 0x8000
	s_cbranch_scc1 .Lps5_spin
.Lps5_rdy:
	buffer_inv sc1
	s_waitcnt vmcnt(0)
	s_mov_b64 exec, -1
.Lps5_w:
	s_barrier
	s_branch .LBB0_491
	s_waitcnt vmcnt(0)
	s_waitcnt vmcnt(0) lgkmcnt(0)
	s_barrier
	s_mov_b64 s[0:1], exec
	v_readlane_b32 s6, v254, 4
	v_readlane_b32 s7, v254, 5
	s_and_b64 s[6:7], s[0:1], s[6:7]
	s_mov_b64 exec, s[6:7]
	s_cbranch_execz .LBB0_490
	s_add_i32 s3, 0, 0x20020
	v_mov_b32_e32 v0, s3
	s_waitcnt vmcnt(0) expcnt(0) lgkmcnt(0)
	ds_read_b32 v2, v0
	s_add_i32 s3, 0, 0x20024
	v_mov_b32_e32 v0, s3
	ds_read_b32 v0, v0
	s_waitcnt lgkmcnt(1)
	v_cmp_ne_u32_e32 vcc, 0, v2
	s_cbranch_vccnz .LBB0_456
	s_add_u32 s6, s94, 0x1200
	s_addc_u32 s7, s95, 0
	s_add_u32 s8, s94, 0x1400
	s_addc_u32 s9, s95, 0
	s_add_u32 s10, s94, 0x1500
	s_addc_u32 s11, s95, 0
	s_add_u32 s12, s94, 0x1600
	s_addc_u32 s13, s95, 0
	s_add_u32 s14, s94, 0x1700
	s_addc_u32 s15, s95, 0
	s_add_u32 s16, s94, 0x1800
	s_addc_u32 s17, s95, 0
	s_add_u32 s20, s94, 0x1900
	s_addc_u32 s21, s95, 0
	s_add_u32 s28, s94, 0x1a00
	s_addc_u32 s29, s95, 0
	s_add_u32 s30, s94, 0x1b00
	s_addc_u32 s31, s95, 0
	s_add_u32 s36, s94, 0x1c00
	s_addc_u32 s37, s95, 0
	s_add_u32 s38, s94, 0x1d00
	s_addc_u32 s39, s95, 0
	s_add_u32 s40, s94, 0x1e00
	s_addc_u32 s41, s95, 0
	s_add_u32 s42, s94, 0x1f00
	s_addc_u32 s43, s95, 0
	s_add_u32 s44, s94, 0x2000
	s_addc_u32 s45, s95, 0
	s_add_u32 s46, s94, 0x2100
	s_addc_u32 s47, s95, 0
	s_add_u32 s48, s94, 0x2200
	s_addc_u32 s49, s95, 0
	s_mul_i32 s3, s35, s75
	s_add_u32 s50, s94, 0x2300
	s_mul_i32 s3, s3, s34
	s_addc_u32 s51, s95, 0
	s_mov_b32 s68, 1
	v_mov_b32_e32 v16, 0
	s_branch .LBB0_444

.LBB0_491:
	s_cmp_lt_i32 s84, 6
	s_cselect_b64 s[0:1], -1, 0
	s_and_b64 s[4:5], s[0:1], s[4:5]
	s_andn2_b64 vcc, exec, s[4:5]
	s_cbranch_vccnz .LBB0_503
	v_lshlrev_b32_e32 v48, 4, v144
	s_waitcnt lgkmcnt(0)
	global_load_dwordx4 v[0:3], v48, s[56:57]
	global_load_dwordx4 v[4:7], v48, s[56:57] offset:1024
	global_load_dwordx4 v[8:11], v48, s[56:57] offset:2048
	global_load_dwordx4 v[12:15], v48, s[56:57] offset:3072
	s_and_b32 s99, s2, 7
	s_lshl_b32 s99, s99, 5
	s_lshr_b32 s3, s2, 3
	s_add_u32 s99, s99, s3
	s_and_b32 s3, s99, 3
	s_lshl_b32 s3, s3, 2
	s_bfe_u32 s0, s99, 0x20002
	s_or_b32 s3, s3, s0
	s_and_b32 s99, s99, 0xfffffff0
	s_or_b32 s99, s99, s3
	v_lshl_add_u32 v50, s99, 3, v145
	s_movk_i32 s0, 0x800
	v_lshlrev_b32_e32 v86, 2, v144
	v_mov_b32_e32 v53, 0
	s_lshl_b32 s30, s34, 3
	v_cmp_gt_i32_e32 vcc, s0, v50
	s_and_saveexec_b64 s[36:37], vcc
	s_cbranch_execz .LBB0_499
	v_mbcnt_lo_u32_b32 v17, -1, 0
	v_mbcnt_hi_u32_b32 v17, -1, v17
	v_and_b32_e32 v18, 64, v17
	v_add_u32_e32 v18, 64, v18
	v_xor_b32_e32 v19, 1, v17
	v_cmp_lt_i32_e32 vcc, v19, v18
	v_lshlrev_b32_e32 v16, 3, v144
	v_mov_b32_e32 v49, v53
	v_cndmask_b32_e32 v19, v17, v19, vcc
	v_lshlrev_b32_e32 v51, 2, v19
	v_xor_b32_e32 v19, 2, v17
	v_cmp_lt_i32_e32 vcc, v19, v18
	v_lshlrev_b32_e32 v52, 5, v144
	v_lshl_add_u64 v[54:55], s[24:25], 0, v[48:49]
	v_cndmask_b32_e32 v19, v17, v19, vcc
	v_lshlrev_b32_e32 v87, 2, v19
	v_xor_b32_e32 v19, 4, v17
	v_cmp_lt_i32_e32 vcc, v19, v18
	v_lshl_add_u64 v[56:57], s[56:57], 0, v[52:53]
	v_lshl_add_u64 v[58:59], s[94:95], 0, v[48:49]
	v_cndmask_b32_e32 v19, v17, v19, vcc
	v_lshlrev_b32_e32 v88, 2, v19
	v_xor_b32_e32 v19, 8, v17
	v_cmp_lt_i32_e32 vcc, v19, v18
	s_lshl_b32 s3, s34, 6
	s_mov_b64 s[48:49], 0
	v_cndmask_b32_e32 v19, v17, v19, vcc
	v_lshlrev_b32_e32 v89, 2, v19
	v_xor_b32_e32 v19, 16, v17
	v_cmp_lt_i32_e32 vcc, v19, v18
	s_mov_b64 s[50:51], 0x4000
	s_mov_b64 s[52:53], 0x3000
	v_cndmask_b32_e32 v19, v17, v19, vcc
	v_lshlrev_b32_e32 v90, 2, v19
	v_xor_b32_e32 v19, 32, v17
	v_cmp_lt_i32_e32 vcc, v19, v18
	v_or_b32_e32 v18, 0x200, v16
	v_lshlrev_b32_e32 v52, 2, v16
	v_cndmask_b32_e32 v17, v17, v19, vcc
	v_lshlrev_b32_e32 v91, 2, v17
	v_lshlrev_b32_e32 v17, 3, v145
	v_lshl_add_u32 v60, s99, 6, v17
	v_lshlrev_b32_e32 v62, 2, v18
	v_mov_b32_e32 v63, v53
	v_lshlrev_b32_e32 v64, 1, v16
	v_mov_b32_e32 v65, v53
	v_mov_b32_e32 v49, 0x358637bd
	s_mov_b32 s8, 0xf800000
	v_mov_b32_e32 v92, 0x260
	s_movk_i32 s9, 0x7ff
	v_mov_b32_e32 v93, v50
	s_branch .LBB0_495

.Ld12_cont:
	s_cmp_gt_i32 s85, 13
	s_cselect_b64 s[4:5], -1, 0
	s_and_b64 s[0:1], s[0:1], s[4:5]
	s_andn2_b64 vcc, exec, s[0:1]
	s_cbranch_vccnz .LBB0_1386
	s_waitcnt vmcnt(0)
	s_barrier
	v_readfirstlane_b32 s3, v145
	s_nop 1
	s_cmp_lg_u32 s3, 0
	s_cbranch_scc1 .Lps13_w
	s_and_b32 s99, s2, 7
	s_lshl_b32 s99, s99, 5
	s_lshr_b32 s3, s2, 3
	s_add_u32 s99, s99, s3
	s_lshr_b32 s3, s99, 4
	s_lshl_b32 s3, s3, 2
	s_and_b32 s99, s99, 3
	s_or_b32 s99, s99, s3
	s_lshl_b32 s99, s99, 2
	s_add_u32 s99, s99, 0x4c00
	s_mov_b64 exec, 1
	v_mov_b32_e32 v0, s99
	v_mov_b32_e32 v1, 1
	global_atomic_add v0, v1, s[94:95]
	s_mov_b32 s99, 0

.Lps13_w:
	s_barrier
	s_branch .LBB0_1386
	s_waitcnt vmcnt(0)
	s_waitcnt vmcnt(0)
	s_barrier
	s_mov_b64 s[0:1], exec
	v_readlane_b32 s6, v254, 4
	v_readlane_b32 s7, v254, 5
	s_and_b64 s[6:7], s[0:1], s[6:7]
	s_mov_b64 exec, s[6:7]
	s_cbranch_execz .LBB0_1385
	s_add_i32 s3, 0, 0x20020
	v_mov_b32_e32 v0, s3
	s_waitcnt vmcnt(0) expcnt(0) lgkmcnt(0)
	ds_read_b32 v2, v0
	s_add_i32 s3, 0, 0x20024
	v_mov_b32_e32 v0, s3
	ds_read_b32 v0, v0
	s_waitcnt lgkmcnt(1)
	v_cmp_ne_u32_e32 vcc, 0, v2
	s_cbranch_vccnz .LBB0_1351
	s_add_u32 s6, s94, 0x1200
	s_addc_u32 s7, s95, 0
	s_add_u32 s8, s94, 0x1400
	s_addc_u32 s9, s95, 0
	s_add_u32 s10, s94, 0x1500
	s_addc_u32 s11, s95, 0
	s_add_u32 s12, s94, 0x1600
	s_addc_u32 s13, s95, 0
	s_add_u32 s14, s94, 0x1700
	s_addc_u32 s15, s95, 0
	s_add_u32 s16, s94, 0x1800
	s_addc_u32 s17, s95, 0
	s_add_u32 s18, s94, 0x1900
	s_addc_u32 s19, s95, 0
	s_add_u32 s20, s94, 0x1a00
	s_addc_u32 s21, s95, 0
	s_add_u32 s24, s94, 0x1b00
	s_addc_u32 s25, s95, 0
	s_add_u32 s26, s94, 0x1c00
	s_addc_u32 s27, s95, 0
	s_add_u32 s28, s94, 0x1d00
	s_addc_u32 s29, s95, 0
	s_add_u32 s30, s94, 0x1e00
	s_addc_u32 s31, s95, 0
	s_add_u32 s36, s94, 0x1f00
	s_addc_u32 s37, s95, 0
	s_add_u32 s38, s94, 0x2000
	s_addc_u32 s39, s95, 0
	s_add_u32 s40, s94, 0x2100
	s_addc_u32 s41, s95, 0
	s_add_u32 s42, s94, 0x2200
	s_addc_u32 s43, s95, 0
	s_mul_i32 s3, s35, s75
	s_add_u32 s44, s94, 0x2300
	s_mul_i32 s3, s3, s34
	s_addc_u32 s45, s95, 0
	s_mov_b32 s52, 1
	v_mov_b32_e32 v16, 0
	s_branch .LBB0_1339

.LBB0_1386:
	s_cmp_lt_i32 s84, 14
	s_cselect_b64 s[0:1], -1, 0
	s_and_b64 s[0:1], s[0:1], s[4:5]
	s_andn2_b64 vcc, exec, s[0:1]
	s_cbranch_vccnz .LBB0_1397
	v_readlane_b32 s4, v254, 0
	v_lshlrev_b32_e32 v48, 4, v144
	v_readlane_b32 s5, v254, 1
	s_nop 4
	global_load_dwordx4 v[0:3], v48, s[4:5]
	global_load_dwordx4 v[4:7], v48, s[4:5] offset:1024
	global_load_dwordx4 v[8:11], v48, s[4:5] offset:2048
	global_load_dwordx4 v[12:15], v48, s[4:5] offset:3072
	s_and_b32 s99, s2, 7
	s_lshl_b32 s99, s99, 5
	s_lshr_b32 s3, s2, 3
	s_add_u32 s99, s99, s3
	s_and_b32 s3, s99, 3
	s_lshl_b32 s3, s3, 2
	s_bfe_u32 s0, s99, 0x20002
	s_or_b32 s3, s3, s0
	s_and_b32 s99, s99, 0xfffffff0
	s_or_b32 s99, s99, s3
	v_lshl_add_u32 v50, s99, 3, v145
	s_movk_i32 s0, 0x800
	s_lshl_b32 s2, s34, 3
	v_cmp_gt_i32_e32 vcc, s0, v50
	v_ashrrev_i32_e32 v51, 31, v50
	v_mbcnt_lo_u32_b32 v49, -1, 0
	v_readlane_b32 s6, v254, 2
	v_readlane_b32 s7, v254, 3
	s_and_saveexec_b64 s[4:5], vcc
	s_cbranch_execz .LBB0_1394
	v_readlane_b32 s8, v254, 0
	v_lshlrev_b32_e32 v52, 5, v144
	v_readlane_b32 s9, v254, 1
	s_nop 4
	global_load_dwordx4 v[16:19], v52, s[8:9] offset:16
	global_load_dwordx4 v[20:23], v52, s[8:9]
	global_load_dwordx4 v[24:27], v52, s[8:9] offset:2064
	global_load_dwordx4 v[28:31], v52, s[8:9] offset:2048
	v_mbcnt_hi_u32_b32 v33, -1, v49
	v_and_b32_e32 v34, 64, v33
	v_add_u32_e32 v34, 64, v34
	v_xor_b32_e32 v35, 1, v33
	v_cmp_lt_i32_e32 vcc, v35, v34
	v_readlane_b32 s10, v254, 2
	v_readlane_b32 s11, v254, 3
	v_cndmask_b32_e32 v35, v33, v35, vcc
	v_lshlrev_b32_e32 v62, 2, v35
	v_xor_b32_e32 v35, 2, v33
	v_cmp_lt_i32_e32 vcc, v35, v34
	v_lshlrev_b32_e32 v32, 3, v144
	v_mov_b32_e32 v53, 0
	v_cndmask_b32_e32 v35, v33, v35, vcc
	v_lshlrev_b32_e32 v63, 2, v35
	v_xor_b32_e32 v35, 4, v33
	v_cmp_lt_i32_e32 vcc, v35, v34
	s_ashr_i32 s3, s2, 31
	v_lshl_add_u64 v[54:55], s[10:11], 0, v[52:53]
	v_cndmask_b32_e32 v35, v33, v35, vcc
	v_lshlrev_b32_e32 v64, 2, v35
	v_xor_b32_e32 v35, 8, v33
	v_cmp_lt_i32_e32 vcc, v35, v34
	s_lshl_b64 s[6:7], s[2:3], 14
	s_mov_b64 s[8:9], 0
	v_cndmask_b32_e32 v35, v33, v35, vcc
	v_lshlrev_b32_e32 v65, 2, v35
	v_xor_b32_e32 v35, 16, v33
	v_cmp_lt_i32_e32 vcc, v35, v34
	v_lshlrev_b32_e32 v52, 1, v32
	v_mov_b32_e32 v68, 0x358637bd
	v_cndmask_b32_e32 v35, v33, v35, vcc
	v_lshlrev_b32_e32 v66, 2, v35
	v_xor_b32_e32 v35, 32, v33
	v_cmp_lt_i32_e32 vcc, v35, v34
	s_mov_b32 s3, 0xf800000
	v_mov_b32_e32 v69, 0x260
	v_cndmask_b32_e32 v33, v33, v35, vcc
	v_lshlrev_b64 v[34:35], 14, v[50:51]
	v_lshl_or_b32 v34, v144, 4, v34
	v_lshlrev_b32_e32 v67, 2, v33
	v_lshl_add_u64 v[56:57], s[94:95], 0, v[34:35]
	s_movk_i32 s16, 0x7ff
	v_mov_b32_e32 v58, v50
	s_branch .LBB0_1390
